# weight conversion loop: counted vmcnt(16) so the first 32-row half is written to LDS while the second half's loads are still in flight
# speedup vs baseline: 1.0017x; 1.0017x over previous
; #define LAS __attribute__((address_space(3)))
; __device__ __forceinline__ void tr_item(const float* src, int ld_src, int k0, int c0, f16* dst, int ld_dst, int r0, int kc0, LAS float* scr, int lane, const float* gk) {
; #pragma unroll 16
;     for (int i = 0; i < 32; ++i) { const int kk = 2 * i + (lane >> 5); scr[kk * 33 + (lane & 31)] = __builtin_nontemporal_load(src + (size_t)(k0 + kk) * ld_src + c0 + (lane & 31)) * (gk ? gk[k0 + kk] : 1.0f); }
.Lwc_noscale:
	v_add_u32_e32 v45, 0x1080, v26
	s_waitcnt vmcnt(16)
	v_mul_f32_e32 v48, v48, v84
	ds_write_b32 v26, v48
	v_mul_f32_e32 v49, v49, v85
	ds_write_b32 v26, v49 offset:264
	v_mul_f32_e32 v50, v50, v86
	ds_write_b32 v26, v50 offset:528
	v_mul_f32_e32 v51, v51, v87
	ds_write_b32 v26, v51 offset:792
	v_mul_f32_e32 v52, v52, v88
	ds_write_b32 v26, v52 offset:1056
	v_mul_f32_e32 v53, v53, v89
	ds_write_b32 v26, v53 offset:1320
	v_mul_f32_e32 v54, v54, v90
	ds_write_b32 v26, v54 offset:1584
	v_mul_f32_e32 v55, v55, v91
	ds_write_b32 v26, v55 offset:1848
	v_mul_f32_e32 v56, v56, v92
	ds_write_b32 v26, v56 offset:2112
	v_mul_f32_e32 v57, v57, v93
	ds_write_b32 v26, v57 offset:2376
	v_mul_f32_e32 v58, v58, v94
	ds_write_b32 v26, v58 offset:2640
	v_mul_f32_e32 v59, v59, v95
	ds_write_b32 v26, v59 offset:2904
	v_mul_f32_e32 v60, v60, v96
	ds_write_b32 v26, v60 offset:3168
	v_mul_f32_e32 v61, v61, v97
	ds_write_b32 v26, v61 offset:3432
	v_mul_f32_e32 v62, v62, v98
	ds_write_b32 v26, v62 offset:3696
	v_mul_f32_e32 v63, v63, v99
	ds_write_b32 v26, v63 offset:3960
	s_waitcnt vmcnt(0)
	v_mul_f32_e32 v64, v64, v100
	ds_write_b32 v45, v64
	v_mul_f32_e32 v65, v65, v101
	ds_write_b32 v45, v65 offset:264
	v_mul_f32_e32 v66, v66, v102
	ds_write_b32 v45, v66 offset:528
	v_mul_f32_e32 v67, v67, v103
	ds_write_b32 v45, v67 offset:792
	v_mul_f32_e32 v68, v68, v104
	ds_write_b32 v45, v68 offset:1056
	v_mul_f32_e32 v69, v69, v105
	ds_write_b32 v45, v69 offset:1320
	v_mul_f32_e32 v70, v70, v106
	ds_write_b32 v45, v70 offset:1584
	v_mul_f32_e32 v71, v71, v107
	ds_write_b32 v45, v71 offset:1848
	v_mul_f32_e32 v72, v72, v108
	ds_write_b32 v45, v72 offset:2112
	v_mul_f32_e32 v73, v73, v109
	ds_write_b32 v45, v73 offset:2376
	v_mul_f32_e32 v74, v74, v110
	ds_write_b32 v45, v74 offset:2640
	v_mul_f32_e32 v75, v75, v111
	ds_write_b32 v45, v75 offset:2904
	v_mul_f32_e32 v76, v76, v112
	ds_write_b32 v45, v76 offset:3168
	v_mul_f32_e32 v77, v77, v113
	ds_write_b32 v45, v77 offset:3432
	v_mul_f32_e32 v78, v78, v114
	ds_write_b32 v45, v78 offset:3696
	v_mul_f32_e32 v79, v79, v115
	ds_write_b32 v45, v79 offset:3960
	s_add_i32 s44, s44, 64
	v_add_u32_e32 v26, 0x2100, v26
	v_lshl_add_u64 v[14:15], v[82:83], 0, s[76:77]
	s_branch .LBB0_20
